# 4-segment + LDS-address loops; the down-projection loop's last two 64-bit VALU address adds replaced by saddr-form LDS-DMA loads (no VALU left in any GEMM main loop)
# baseline (speedup 1.0000x reference)
.LBB0_37:
	s_add_i32 s69, s48, 2
	s_add_u32 s46, s0, 0x100
	s_addc_u32 s47, s1, 0
	s_add_i32 s70, 0, 0x10000
	ds_read_b128 v[140:143], v153
	ds_read_b128 v[144:147], v153 offset:1024
	ds_read_b128 v[148:151], v153 offset:2048
	ds_read_b128 v[168:171], v153 offset:3072
	s_cmp_eq_u32 s12, s48
	s_cselect_b32 s48, s44, s13
	s_cselect_b32 s51, s43, s47
	s_cselect_b32 s50, s42, s46
	s_cselect_b32 s49, s45, s68
	ds_read_b128 v[172:175], v155
	ds_read_b128 v[176:179], v155 offset:1024
	ds_read_b128 v[180:183], v155 offset:2048
	ds_read_b128 v[184:187], v155 offset:3072
	ds_read_b128 v[188:191], v155 offset:4096
	ds_read_b128 v[192:195], v155 offset:5120
	ds_read_b128 v[196:199], v155 offset:6144
	ds_read_b128 v[224:227], v155 offset:7168
	s_add_i32 m0, s53, 0xc000
	s_nop 0
	global_load_lds_dwordx4 v136, s[0:1]
	s_add_i32 m0, s53, 0xe000
	s_nop 0
	global_load_lds_dwordx4 v138, s[0:1]
	s_add_i32 s71, 0, 0x14000
	s_add_i32 s0, s70, s52
	ds_read_b128 v[228:231], v153 offset:16384
	ds_read_b128 v[232:235], v153 offset:17408
	ds_read_b128 v[236:239], v153 offset:18432
	ds_read_b128 v[240:243], v153 offset:19456
	s_waitcnt lgkmcnt(0)
	s_barrier
	v_mfma_f32_16x16x32_bf16 v[126:129], v[140:143], v[172:175], v[126:129]
	v_mfma_f32_16x16x32_bf16 v[122:125], v[148:151], v[172:175], v[122:125]
	v_mfma_f32_16x16x32_bf16 v[110:113], v[140:143], v[180:183], v[110:113]
	v_mfma_f32_16x16x32_bf16 v[106:109], v[148:151], v[180:183], v[106:109]
	v_mfma_f32_16x16x32_bf16 v[94:97], v[140:143], v[188:191], v[94:97]
	v_mfma_f32_16x16x32_bf16 v[90:93], v[148:151], v[188:191], v[90:93]
	v_mfma_f32_16x16x32_bf16 v[78:81], v[140:143], v[196:199], v[78:81]
	v_mfma_f32_16x16x32_bf16 v[74:77], v[148:151], v[196:199], v[74:77]
	v_mfma_f32_16x16x32_bf16 v[126:129], v[144:147], v[176:179], v[126:129]
	v_mfma_f32_16x16x32_bf16 v[122:125], v[168:171], v[176:179], v[122:125]
	v_mfma_f32_16x16x32_bf16 v[110:113], v[144:147], v[184:187], v[110:113]
	v_mfma_f32_16x16x32_bf16 v[106:109], v[168:171], v[184:187], v[106:109]
	v_mfma_f32_16x16x32_bf16 v[94:97], v[144:147], v[192:195], v[94:97]
	v_mfma_f32_16x16x32_bf16 v[90:93], v[168:171], v[192:195], v[90:93]
	v_mfma_f32_16x16x32_bf16 v[78:81], v[144:147], v[224:227], v[78:81]
	v_mfma_f32_16x16x32_bf16 v[74:77], v[168:171], v[224:227], v[74:77]
	v_mfma_f32_16x16x32_bf16 v[118:121], v[228:231], v[172:175], v[118:121]
	v_mfma_f32_16x16x32_bf16 v[114:117], v[236:239], v[172:175], v[114:117]
	v_mfma_f32_16x16x32_bf16 v[102:105], v[228:231], v[180:183], v[102:105]
	v_mfma_f32_16x16x32_bf16 v[98:101], v[236:239], v[180:183], v[98:101]
	v_mfma_f32_16x16x32_bf16 v[86:89], v[228:231], v[188:191], v[86:89]
	v_mfma_f32_16x16x32_bf16 v[82:85], v[236:239], v[188:191], v[82:85]
	v_mfma_f32_16x16x32_bf16 v[70:73], v[228:231], v[196:199], v[70:73]
	v_mfma_f32_16x16x32_bf16 v[66:69], v[236:239], v[196:199], v[66:69]
	v_mfma_f32_16x16x32_bf16 v[118:121], v[232:235], v[176:179], v[118:121]
	v_mfma_f32_16x16x32_bf16 v[114:117], v[240:243], v[176:179], v[114:117]
	v_mfma_f32_16x16x32_bf16 v[102:105], v[232:235], v[184:187], v[102:105]
	v_mfma_f32_16x16x32_bf16 v[98:101], v[240:243], v[184:187], v[98:101]
	v_mfma_f32_16x16x32_bf16 v[86:89], v[232:235], v[192:195], v[86:89]
	v_mfma_f32_16x16x32_bf16 v[82:85], v[240:243], v[192:195], v[82:85]
	v_mfma_f32_16x16x32_bf16 v[70:73], v[232:235], v[224:227], v[70:73]
	v_mfma_f32_16x16x32_bf16 v[66:69], v[240:243], v[224:227], v[66:69]
	s_barrier
	s_mov_b32 m0, s53
	s_add_u32 s78, s50, s94
	s_addc_u32 s79, s51, s95
	ds_read_b128 v[172:175], v155 offset:16384
	ds_read_b128 v[176:179], v155 offset:17408
	ds_read_b128 v[180:183], v155 offset:18432
	ds_read_b128 v[184:187], v155 offset:19456
	ds_read_b128 v[188:191], v155 offset:20480
	ds_read_b128 v[192:195], v155 offset:21504
	ds_read_b128 v[196:199], v155 offset:22528
	ds_read_b128 v[224:227], v155 offset:23552
	global_load_lds_dwordx4 v134, s[50:51]
	s_mov_b32 m0, s54
	s_nop 0
	global_load_lds_dwordx4 v132, s[50:51]
	s_add_u32 s76, s48, s94
	s_addc_u32 s77, s49, s95
	s_mov_b32 m0, s0
	s_nop 0
	global_load_lds_dwordx4 v0, s[48:49]
	s_add_i32 m0, s0, 0x2000
	s_nop 0
	global_load_lds_dwordx4 v130, s[48:49]
	s_add_u32 s0, s48, 0x160000
	s_addc_u32 s1, s49, 0
	s_add_i32 s70, s71, s52
	s_mov_b32 m0, s70
	s_nop 0
	global_load_lds_dwordx4 v0, s[0:1]
	s_add_i32 m0, s70, 0x2000
	s_nop 0
	global_load_lds_dwordx4 v130, s[0:1]
	s_waitcnt vmcnt(6) lgkmcnt(0)
	s_barrier
	v_mfma_f32_16x16x32_bf16 v[62:65], v[140:143], v[172:175], v[62:65]
	v_mfma_f32_16x16x32_bf16 v[58:61], v[148:151], v[172:175], v[58:61]
	v_mfma_f32_16x16x32_bf16 v[46:49], v[140:143], v[180:183], v[46:49]
	v_mfma_f32_16x16x32_bf16 v[42:45], v[148:151], v[180:183], v[42:45]
	v_mfma_f32_16x16x32_bf16 v[30:33], v[140:143], v[188:191], v[30:33]
	v_mfma_f32_16x16x32_bf16 v[26:29], v[148:151], v[188:191], v[26:29]
	v_mfma_f32_16x16x32_bf16 v[14:17], v[140:143], v[196:199], v[14:17]
	v_mfma_f32_16x16x32_bf16 v[10:13], v[148:151], v[196:199], v[10:13]
	v_mfma_f32_16x16x32_bf16 v[62:65], v[144:147], v[176:179], v[62:65]
	v_mfma_f32_16x16x32_bf16 v[58:61], v[168:171], v[176:179], v[58:61]
	v_mfma_f32_16x16x32_bf16 v[46:49], v[144:147], v[184:187], v[46:49]
	v_mfma_f32_16x16x32_bf16 v[42:45], v[168:171], v[184:187], v[42:45]
	v_mfma_f32_16x16x32_bf16 v[30:33], v[144:147], v[192:195], v[30:33]
	v_mfma_f32_16x16x32_bf16 v[26:29], v[168:171], v[192:195], v[26:29]
	v_mfma_f32_16x16x32_bf16 v[14:17], v[144:147], v[224:227], v[14:17]
	v_mfma_f32_16x16x32_bf16 v[10:13], v[168:171], v[224:227], v[10:13]
	v_mfma_f32_16x16x32_bf16 v[54:57], v[228:231], v[172:175], v[54:57]
	v_mfma_f32_16x16x32_bf16 v[50:53], v[236:239], v[172:175], v[50:53]
	v_mfma_f32_16x16x32_bf16 v[38:41], v[228:231], v[180:183], v[38:41]
	v_mfma_f32_16x16x32_bf16 v[34:37], v[236:239], v[180:183], v[34:37]
	v_mfma_f32_16x16x32_bf16 v[22:25], v[228:231], v[188:191], v[22:25]
	v_mfma_f32_16x16x32_bf16 v[18:21], v[236:239], v[188:191], v[18:21]
	v_mfma_f32_16x16x32_bf16 v[6:9], v[228:231], v[196:199], v[6:9]
	v_mfma_f32_16x16x32_bf16 v[2:5], v[236:239], v[196:199], v[2:5]
	v_mfma_f32_16x16x32_bf16 v[54:57], v[232:235], v[176:179], v[54:57]
	v_mfma_f32_16x16x32_bf16 v[50:53], v[240:243], v[176:179], v[50:53]
	v_mfma_f32_16x16x32_bf16 v[38:41], v[232:235], v[184:187], v[38:41]
	v_mfma_f32_16x16x32_bf16 v[34:37], v[240:243], v[184:187], v[34:37]
	v_mfma_f32_16x16x32_bf16 v[22:25], v[232:235], v[192:195], v[22:25]
	v_mfma_f32_16x16x32_bf16 v[18:21], v[240:243], v[192:195], v[18:21]
	v_mfma_f32_16x16x32_bf16 v[6:9], v[232:235], v[224:227], v[6:9]
	v_mfma_f32_16x16x32_bf16 v[2:5], v[240:243], v[224:227], v[2:5]
	s_barrier
	s_add_i32 s70, 0, 0x18000
	ds_read_b128 v[140:143], v153 offset:32768
	ds_read_b128 v[144:147], v153 offset:33792
	ds_read_b128 v[148:151], v153 offset:34816
	ds_read_b128 v[168:171], v153 offset:35840
	s_add_u32 s0, s50, 0x2c0000
	s_addc_u32 s1, s51, 0
	ds_read_b128 v[172:175], v155 offset:32768
	ds_read_b128 v[176:179], v155 offset:33792
	ds_read_b128 v[180:183], v155 offset:34816
	ds_read_b128 v[184:187], v155 offset:35840
	ds_read_b128 v[188:191], v155 offset:36864
	ds_read_b128 v[192:195], v155 offset:37888
	ds_read_b128 v[196:199], v155 offset:38912
	ds_read_b128 v[224:227], v155 offset:39936
	s_mov_b32 m0, s55
	s_nop 0
	global_load_lds_dwordx4 v134, s[0:1]
	s_mov_b32 m0, s56
	s_nop 0
	global_load_lds_dwordx4 v132, s[0:1]
	s_add_i32 s50, 0, 0x1c000
	s_add_i32 s0, s70, s52
	ds_read_b128 v[228:231], v153 offset:49152
	ds_read_b128 v[232:235], v153 offset:50176
	ds_read_b128 v[236:239], v153 offset:51200
	ds_read_b128 v[240:243], v153 offset:52224
	s_waitcnt lgkmcnt(0)
	s_barrier
	v_mfma_f32_16x16x32_bf16 v[126:129], v[140:143], v[172:175], v[126:129]
	v_mfma_f32_16x16x32_bf16 v[122:125], v[148:151], v[172:175], v[122:125]
	v_mfma_f32_16x16x32_bf16 v[110:113], v[140:143], v[180:183], v[110:113]
	v_mfma_f32_16x16x32_bf16 v[106:109], v[148:151], v[180:183], v[106:109]
	v_mfma_f32_16x16x32_bf16 v[94:97], v[140:143], v[188:191], v[94:97]
	v_mfma_f32_16x16x32_bf16 v[90:93], v[148:151], v[188:191], v[90:93]
	v_mfma_f32_16x16x32_bf16 v[78:81], v[140:143], v[196:199], v[78:81]
	v_mfma_f32_16x16x32_bf16 v[74:77], v[148:151], v[196:199], v[74:77]
	v_mfma_f32_16x16x32_bf16 v[126:129], v[144:147], v[176:179], v[126:129]
	v_mfma_f32_16x16x32_bf16 v[122:125], v[168:171], v[176:179], v[122:125]
	v_mfma_f32_16x16x32_bf16 v[110:113], v[144:147], v[184:187], v[110:113]
	v_mfma_f32_16x16x32_bf16 v[106:109], v[168:171], v[184:187], v[106:109]
	v_mfma_f32_16x16x32_bf16 v[94:97], v[144:147], v[192:195], v[94:97]
	v_mfma_f32_16x16x32_bf16 v[90:93], v[168:171], v[192:195], v[90:93]
	v_mfma_f32_16x16x32_bf16 v[78:81], v[144:147], v[224:227], v[78:81]
	v_mfma_f32_16x16x32_bf16 v[74:77], v[168:171], v[224:227], v[74:77]
	v_mfma_f32_16x16x32_bf16 v[118:121], v[228:231], v[172:175], v[118:121]
	v_mfma_f32_16x16x32_bf16 v[114:117], v[236:239], v[172:175], v[114:117]
	v_mfma_f32_16x16x32_bf16 v[102:105], v[228:231], v[180:183], v[102:105]
	v_mfma_f32_16x16x32_bf16 v[98:101], v[236:239], v[180:183], v[98:101]
	v_mfma_f32_16x16x32_bf16 v[86:89], v[228:231], v[188:191], v[86:89]
	v_mfma_f32_16x16x32_bf16 v[82:85], v[236:239], v[188:191], v[82:85]
	v_mfma_f32_16x16x32_bf16 v[70:73], v[228:231], v[196:199], v[70:73]
	v_mfma_f32_16x16x32_bf16 v[66:69], v[236:239], v[196:199], v[66:69]
	v_mfma_f32_16x16x32_bf16 v[118:121], v[232:235], v[176:179], v[118:121]
	v_mfma_f32_16x16x32_bf16 v[114:117], v[240:243], v[176:179], v[114:117]
	v_mfma_f32_16x16x32_bf16 v[102:105], v[232:235], v[184:187], v[102:105]
	v_mfma_f32_16x16x32_bf16 v[98:101], v[240:243], v[184:187], v[98:101]
	v_mfma_f32_16x16x32_bf16 v[86:89], v[232:235], v[192:195], v[86:89]
	v_mfma_f32_16x16x32_bf16 v[82:85], v[240:243], v[192:195], v[82:85]
	v_mfma_f32_16x16x32_bf16 v[70:73], v[232:235], v[224:227], v[70:73]
	v_mfma_f32_16x16x32_bf16 v[66:69], v[240:243], v[224:227], v[66:69]
	s_barrier
	s_mov_b32 m0, s57
	ds_read_b128 v[172:175], v155 offset:49152
	ds_read_b128 v[176:179], v155 offset:50176
	ds_read_b128 v[180:183], v155 offset:51200
	ds_read_b128 v[184:187], v155 offset:52224
	ds_read_b128 v[188:191], v155 offset:53248
	ds_read_b128 v[192:195], v155 offset:54272
	ds_read_b128 v[196:199], v155 offset:55296
	ds_read_b128 v[224:227], v155 offset:56320
	global_load_lds_dwordx4 v134, s[78:79]
	s_mov_b32 m0, s58
	s_nop 0
	global_load_lds_dwordx4 v132, s[78:79]
	s_mov_b32 m0, s0
	s_nop 0
	global_load_lds_dwordx4 v0, s[76:77]
	s_add_i32 m0, s0, 0x2000
	s_nop 0
	global_load_lds_dwordx4 v130, s[76:77]
	s_add_u32 s0, s48, 0x160080
	s_addc_u32 s1, s49, 0
	s_add_i32 s48, s50, s52
	s_mov_b32 m0, s48
	s_nop 0
	global_load_lds_dwordx4 v0, s[0:1]
	s_add_i32 m0, s48, 0x2000
	s_nop 0
	global_load_lds_dwordx4 v130, s[0:1]
	s_waitcnt vmcnt(6) lgkmcnt(0)
	s_barrier
	v_mfma_f32_16x16x32_bf16 v[62:65], v[140:143], v[172:175], v[62:65]
	v_mfma_f32_16x16x32_bf16 v[58:61], v[148:151], v[172:175], v[58:61]
	v_mfma_f32_16x16x32_bf16 v[46:49], v[140:143], v[180:183], v[46:49]
	v_mfma_f32_16x16x32_bf16 v[42:45], v[148:151], v[180:183], v[42:45]
	v_mfma_f32_16x16x32_bf16 v[30:33], v[140:143], v[188:191], v[30:33]
	v_mfma_f32_16x16x32_bf16 v[26:29], v[148:151], v[188:191], v[26:29]
	v_mfma_f32_16x16x32_bf16 v[14:17], v[140:143], v[196:199], v[14:17]
	v_mfma_f32_16x16x32_bf16 v[10:13], v[148:151], v[196:199], v[10:13]
	v_mfma_f32_16x16x32_bf16 v[62:65], v[144:147], v[176:179], v[62:65]
	v_mfma_f32_16x16x32_bf16 v[58:61], v[168:171], v[176:179], v[58:61]
	v_mfma_f32_16x16x32_bf16 v[46:49], v[144:147], v[184:187], v[46:49]
	v_mfma_f32_16x16x32_bf16 v[42:45], v[168:171], v[184:187], v[42:45]
	v_mfma_f32_16x16x32_bf16 v[30:33], v[144:147], v[192:195], v[30:33]
	v_mfma_f32_16x16x32_bf16 v[26:29], v[168:171], v[192:195], v[26:29]
	v_mfma_f32_16x16x32_bf16 v[14:17], v[144:147], v[224:227], v[14:17]
	v_mfma_f32_16x16x32_bf16 v[10:13], v[168:171], v[224:227], v[10:13]
	v_mfma_f32_16x16x32_bf16 v[54:57], v[228:231], v[172:175], v[54:57]
	v_mfma_f32_16x16x32_bf16 v[50:53], v[236:239], v[172:175], v[50:53]
	v_mfma_f32_16x16x32_bf16 v[38:41], v[228:231], v[180:183], v[38:41]
	v_mfma_f32_16x16x32_bf16 v[34:37], v[236:239], v[180:183], v[34:37]
	v_mfma_f32_16x16x32_bf16 v[22:25], v[228:231], v[188:191], v[22:25]
	v_mfma_f32_16x16x32_bf16 v[18:21], v[236:239], v[188:191], v[18:21]
	v_mfma_f32_16x16x32_bf16 v[6:9], v[228:231], v[196:199], v[6:9]
	v_mfma_f32_16x16x32_bf16 v[2:5], v[236:239], v[196:199], v[2:5]
	v_mfma_f32_16x16x32_bf16 v[54:57], v[232:235], v[176:179], v[54:57]
	v_mfma_f32_16x16x32_bf16 v[50:53], v[240:243], v[176:179], v[50:53]
	v_mfma_f32_16x16x32_bf16 v[38:41], v[232:235], v[184:187], v[38:41]
	v_mfma_f32_16x16x32_bf16 v[34:37], v[240:243], v[184:187], v[34:37]
	v_mfma_f32_16x16x32_bf16 v[22:25], v[232:235], v[192:195], v[22:25]
	v_mfma_f32_16x16x32_bf16 v[18:21], v[240:243], v[192:195], v[18:21]
	v_mfma_f32_16x16x32_bf16 v[6:9], v[232:235], v[224:227], v[6:9]
	v_mfma_f32_16x16x32_bf16 v[2:5], v[240:243], v[224:227], v[2:5]
	s_barrier
	s_add_u32 s13, s13, 0x100
	s_addc_u32 s68, s68, 0
	s_mov_b64 s[0:1], s[46:47]
	s_mov_b32 s48, s69
	s_cmp_ge_i32 s69, s39
	s_cbranch_scc0 .LBB0_37
	s_cmp_eq_u32 s65, 2
	s_cbranch_scc1 .Lepi10_orig
	v_readlane_b32 s90, v255, 17
	v_readlane_b32 s91, v255, 18
	v_readlane_b32 s96, v255, 19
	v_readlane_b32 s97, v255, 20
	v_lshl_or_b32 v156, s66, 8, v154
	v_lshlrev_b32_e32 v156, 2, v156
	v_lshl_add_u32 v157, v152, 13, v156
	s_lshl_b32 s72, s67, 21
	s_add_u32 s74, s22, s72
	s_addc_u32 s75, s23, 0
	s_add_u32 s76, s22, s72
	s_addc_u32 s77, s23, 0
	s_lshr_b32 s73, s67, 3
	s_mul_i32 s73, s73, 0xc000
	s_add_u32 s73, s73, 0xa000
	s_add_u32 s70, s90, s73
	s_addc_u32 s71, s91, 0
	global_load_dwordx4 v[140:143], v156, s[70:71]
	global_load_dwordx4 v[144:147], v156, s[70:71] offset:64
	global_load_dwordx4 v[148:151], v156, s[70:71] offset:512
	global_load_dwordx4 v[168:171], v156, s[70:71] offset:576
	global_load_dwordx4 v[224:227], v157, s[74:75] nt
	global_load_dwordx4 v[228:231], v157, s[74:75] offset:64 nt
	global_load_dwordx4 v[232:235], v157, s[74:75] offset:512 nt
	global_load_dwordx4 v[236:239], v157, s[74:75] offset:576 nt
	s_add_u32 s74, s74, 0x20000
	s_addc_u32 s75, s75, 0
	global_load_dwordx4 v[240:243], v157, s[74:75] nt
	global_load_dwordx4 v[244:247], v157, s[74:75] offset:64 nt
	s_waitcnt vmcnt(5)
	v_pk_fma_f32 v[128:129], v[128:129], v[142:143], v[226:227]
	v_pk_fma_f32 v[126:127], v[126:127], v[140:141], v[224:225]
	global_store_dwordx4 v157, v[126:129], s[76:77] nt
	global_load_dwordx4 v[224:227], v157, s[74:75] offset:512 nt
	s_waitcnt vmcnt(6)
	v_pk_fma_f32 v[124:125], v[124:125], v[146:147], v[230:231]
	v_pk_fma_f32 v[122:123], v[122:123], v[144:145], v[228:229]
	global_store_dwordx4 v157, v[122:125], s[76:77] offset:64 nt
	global_load_dwordx4 v[228:231], v157, s[74:75] offset:576 nt
	s_waitcnt vmcnt(7)
	v_pk_fma_f32 v[120:121], v[120:121], v[150:151], v[234:235]
	v_pk_fma_f32 v[118:119], v[118:119], v[148:149], v[232:233]
	global_store_dwordx4 v157, v[118:121], s[76:77] offset:512 nt
	s_add_u32 s74, s74, 0x20000
	s_addc_u32 s75, s75, 0
	global_load_dwordx4 v[232:235], v157, s[74:75] nt
	s_waitcnt vmcnt(8)
	v_pk_fma_f32 v[116:117], v[116:117], v[170:171], v[238:239]
	v_pk_fma_f32 v[114:115], v[114:115], v[168:169], v[236:237]
	global_store_dwordx4 v157, v[114:117], s[76:77] offset:576 nt
	global_load_dwordx4 v[236:239], v157, s[74:75] offset:64 nt
	s_add_u32 s76, s76, 0x20000
	s_addc_u32 s77, s77, 0
	s_waitcnt vmcnt(9)
	v_pk_fma_f32 v[112:113], v[112:113], v[142:143], v[242:243]
	v_pk_fma_f32 v[110:111], v[110:111], v[140:141], v[240:241]
	global_store_dwordx4 v157, v[110:113], s[76:77] nt
	global_load_dwordx4 v[240:243], v157, s[74:75] offset:512 nt
	s_waitcnt vmcnt(10)
	v_pk_fma_f32 v[108:109], v[108:109], v[146:147], v[246:247]
	v_pk_fma_f32 v[106:107], v[106:107], v[144:145], v[244:245]
	global_store_dwordx4 v157, v[106:109], s[76:77] offset:64 nt
	global_load_dwordx4 v[244:247], v157, s[74:75] offset:576 nt
	s_waitcnt vmcnt(10)
	v_pk_fma_f32 v[104:105], v[104:105], v[150:151], v[226:227]
	v_pk_fma_f32 v[102:103], v[102:103], v[148:149], v[224:225]
	global_store_dwordx4 v157, v[102:105], s[76:77] offset:512 nt
	s_add_u32 s74, s74, 0x20000
	s_addc_u32 s75, s75, 0
	global_load_dwordx4 v[224:227], v157, s[74:75] nt
	s_waitcnt vmcnt(10)
	v_pk_fma_f32 v[100:101], v[100:101], v[170:171], v[230:231]
	v_pk_fma_f32 v[98:99], v[98:99], v[168:169], v[228:229]
	global_store_dwordx4 v157, v[98:101], s[76:77] offset:576 nt
	global_load_dwordx4 v[228:231], v157, s[74:75] offset:64 nt
	s_add_u32 s76, s76, 0x20000
	s_addc_u32 s77, s77, 0
	s_waitcnt vmcnt(10)
	v_pk_fma_f32 v[96:97], v[96:97], v[142:143], v[234:235]
	v_pk_fma_f32 v[94:95], v[94:95], v[140:141], v[232:233]
	global_store_dwordx4 v157, v[94:97], s[76:77] nt
	global_load_dwordx4 v[232:235], v157, s[74:75] offset:512 nt
	s_waitcnt vmcnt(10)
	v_pk_fma_f32 v[92:93], v[92:93], v[146:147], v[238:239]
	v_pk_fma_f32 v[90:91], v[90:91], v[144:145], v[236:237]
	global_store_dwordx4 v157, v[90:93], s[76:77] offset:64 nt
	global_load_dwordx4 v[236:239], v157, s[74:75] offset:576 nt
	s_waitcnt vmcnt(10)
	v_pk_fma_f32 v[88:89], v[88:89], v[150:151], v[242:243]
	v_pk_fma_f32 v[86:87], v[86:87], v[148:149], v[240:241]
	global_store_dwordx4 v157, v[86:89], s[76:77] offset:512 nt
	s_add_u32 s74, s74, 0xa0000
	s_addc_u32 s75, s75, 0
	global_load_dwordx4 v[240:243], v157, s[74:75] nt
	s_waitcnt vmcnt(10)
	v_pk_fma_f32 v[84:85], v[84:85], v[170:171], v[246:247]
	v_pk_fma_f32 v[82:83], v[82:83], v[168:169], v[244:245]
	global_store_dwordx4 v157, v[82:85], s[76:77] offset:576 nt
	global_load_dwordx4 v[244:247], v157, s[74:75] offset:64 nt
	s_add_u32 s76, s76, 0x20000
	s_addc_u32 s77, s77, 0
	s_waitcnt vmcnt(10)
	v_pk_fma_f32 v[80:81], v[80:81], v[142:143], v[226:227]
	v_pk_fma_f32 v[78:79], v[78:79], v[140:141], v[224:225]
	global_store_dwordx4 v157, v[78:81], s[76:77] nt
	global_load_dwordx4 v[224:227], v157, s[74:75] offset:512 nt
	s_waitcnt vmcnt(10)
	v_pk_fma_f32 v[76:77], v[76:77], v[146:147], v[230:231]
	v_pk_fma_f32 v[74:75], v[74:75], v[144:145], v[228:229]
	global_store_dwordx4 v157, v[74:77], s[76:77] offset:64 nt
	global_load_dwordx4 v[228:231], v157, s[74:75] offset:576 nt
	s_waitcnt vmcnt(10)
	v_pk_fma_f32 v[72:73], v[72:73], v[150:151], v[234:235]
	v_pk_fma_f32 v[70:71], v[70:71], v[148:149], v[232:233]
	global_store_dwordx4 v157, v[70:73], s[76:77] offset:512 nt
	s_add_u32 s74, s74, 0x20000
	s_addc_u32 s75, s75, 0
	global_load_dwordx4 v[232:235], v157, s[74:75] nt
	s_waitcnt vmcnt(10)
	v_pk_fma_f32 v[68:69], v[68:69], v[170:171], v[238:239]
	v_pk_fma_f32 v[66:67], v[66:67], v[168:169], v[236:237]
	global_store_dwordx4 v157, v[66:69], s[76:77] offset:576 nt
	global_load_dwordx4 v[236:239], v157, s[74:75] offset:64 nt
	s_add_u32 s76, s76, 0xa0000
	s_addc_u32 s77, s77, 0
	s_waitcnt vmcnt(10)
	v_pk_fma_f32 v[64:65], v[64:65], v[142:143], v[242:243]
	v_pk_fma_f32 v[62:63], v[62:63], v[140:141], v[240:241]
	global_store_dwordx4 v157, v[62:65], s[76:77] nt
	global_load_dwordx4 v[240:243], v157, s[74:75] offset:512 nt
	s_waitcnt vmcnt(10)
	v_pk_fma_f32 v[60:61], v[60:61], v[146:147], v[246:247]
	v_pk_fma_f32 v[58:59], v[58:59], v[144:145], v[244:245]
	global_store_dwordx4 v157, v[58:61], s[76:77] offset:64 nt
	global_load_dwordx4 v[244:247], v157, s[74:75] offset:576 nt
	s_waitcnt vmcnt(10)
	v_pk_fma_f32 v[56:57], v[56:57], v[150:151], v[226:227]
	v_pk_fma_f32 v[54:55], v[54:55], v[148:149], v[224:225]
	global_store_dwordx4 v157, v[54:57], s[76:77] offset:512 nt
	s_add_u32 s74, s74, 0x20000
	s_addc_u32 s75, s75, 0
	global_load_dwordx4 v[224:227], v157, s[74:75] nt
	s_waitcnt vmcnt(10)
	v_pk_fma_f32 v[52:53], v[52:53], v[170:171], v[230:231]
	v_pk_fma_f32 v[50:51], v[50:51], v[168:169], v[228:229]
	global_store_dwordx4 v157, v[50:53], s[76:77] offset:576 nt
	global_load_dwordx4 v[228:231], v157, s[74:75] offset:64 nt
	s_add_u32 s76, s76, 0x20000
	s_addc_u32 s77, s77, 0
	s_waitcnt vmcnt(10)
	v_pk_fma_f32 v[48:49], v[48:49], v[142:143], v[234:235]
	v_pk_fma_f32 v[46:47], v[46:47], v[140:141], v[232:233]
	global_store_dwordx4 v157, v[46:49], s[76:77] nt
	global_load_dwordx4 v[232:235], v157, s[74:75] offset:512 nt
	s_waitcnt vmcnt(10)
	v_pk_fma_f32 v[44:45], v[44:45], v[146:147], v[238:239]
	v_pk_fma_f32 v[42:43], v[42:43], v[144:145], v[236:237]
	global_store_dwordx4 v157, v[42:45], s[76:77] offset:64 nt
	global_load_dwordx4 v[236:239], v157, s[74:75] offset:576 nt
	s_waitcnt vmcnt(10)
	v_pk_fma_f32 v[40:41], v[40:41], v[150:151], v[242:243]
	v_pk_fma_f32 v[38:39], v[38:39], v[148:149], v[240:241]
	global_store_dwordx4 v157, v[38:41], s[76:77] offset:512 nt
	s_add_u32 s74, s74, 0x20000
	s_addc_u32 s75, s75, 0
	global_load_dwordx4 v[240:243], v157, s[74:75] nt
	s_waitcnt vmcnt(10)
	v_pk_fma_f32 v[36:37], v[36:37], v[170:171], v[246:247]
	v_pk_fma_f32 v[34:35], v[34:35], v[168:169], v[244:245]
	global_store_dwordx4 v157, v[34:37], s[76:77] offset:576 nt
	global_load_dwordx4 v[244:247], v157, s[74:75] offset:64 nt
	s_add_u32 s76, s76, 0x20000
	s_addc_u32 s77, s77, 0
	s_waitcnt vmcnt(10)
	v_pk_fma_f32 v[32:33], v[32:33], v[142:143], v[226:227]
	v_pk_fma_f32 v[30:31], v[30:31], v[140:141], v[224:225]
	global_store_dwordx4 v157, v[30:33], s[76:77] nt
	global_load_dwordx4 v[224:227], v157, s[74:75] offset:512 nt
	s_waitcnt vmcnt(10)
	v_pk_fma_f32 v[28:29], v[28:29], v[146:147], v[230:231]
	v_pk_fma_f32 v[26:27], v[26:27], v[144:145], v[228:229]
	global_store_dwordx4 v157, v[26:29], s[76:77] offset:64 nt
	global_load_dwordx4 v[228:231], v157, s[74:75] offset:576 nt
	s_waitcnt vmcnt(10)
	v_pk_fma_f32 v[24:25], v[24:25], v[150:151], v[234:235]
	v_pk_fma_f32 v[22:23], v[22:23], v[148:149], v[232:233]
	global_store_dwordx4 v157, v[22:25], s[76:77] offset:512 nt
	s_waitcnt vmcnt(9)
	v_pk_fma_f32 v[20:21], v[20:21], v[170:171], v[238:239]
	v_pk_fma_f32 v[18:19], v[18:19], v[168:169], v[236:237]
	global_store_dwordx4 v157, v[18:21], s[76:77] offset:576 nt
	s_add_u32 s76, s76, 0x20000
	s_addc_u32 s77, s77, 0
	s_waitcnt vmcnt(8)
	v_pk_fma_f32 v[16:17], v[16:17], v[142:143], v[242:243]
	v_pk_fma_f32 v[14:15], v[14:15], v[140:141], v[240:241]
	global_store_dwordx4 v157, v[14:17], s[76:77] nt
	s_waitcnt vmcnt(7)
	v_pk_fma_f32 v[12:13], v[12:13], v[146:147], v[246:247]
	v_pk_fma_f32 v[10:11], v[10:11], v[144:145], v[244:245]
	global_store_dwordx4 v157, v[10:13], s[76:77] offset:64 nt
	s_waitcnt vmcnt(6)
	v_pk_fma_f32 v[8:9], v[8:9], v[150:151], v[226:227]
	v_pk_fma_f32 v[6:7], v[6:7], v[148:149], v[224:225]
	global_store_dwordx4 v157, v[6:9], s[76:77] offset:512 nt
	s_waitcnt vmcnt(5)
	v_pk_fma_f32 v[4:5], v[4:5], v[170:171], v[230:231]
	v_pk_fma_f32 v[2:3], v[2:3], v[168:169], v[228:229]
	global_store_dwordx4 v157, v[2:5], s[76:77] offset:576 nt
	s_branch .LBB0_24
